# layer-0 out-projection residual epilogue (f32 input rows): 16 cache-warming loads for all row groups issued at epilogue entry so the 16 serialised load/drain/store steps hit L2 instead of memory
# speedup vs baseline: 1.0103x; 1.0035x over previous
.LBB0_1940:
	v_add_u32_e32 v156, s26, v167
	v_ashrrev_i32_e32 v157, 31, v156
	v_lshlrev_b64 v[128:129], 11, v[156:157]
	v_cndmask_b32_e64 v130, 0, 1, s[54:55]
	v_cmp_ne_u32_e64 s[36:37], 1, v130
	s_andn2_b64 vcc, exec, s[54:55]
	v_lshl_add_u64 v[160:161], v[128:129], 2, s[38:39]
	s_cbranch_vccnz .LBB0_1943
	v_lshlrev_b32_e32 v188, 13, v156
	v_lshl_add_u32 v188, v154, 2, v188
	global_load_dword v172, v188, s[38:39]
	global_load_dword v173, v188, s[38:39] offset:512
	s_add_u32 s98, s38, 0x20000
	s_addc_u32 s99, s39, 0
	global_load_dword v174, v188, s[98:99]
	global_load_dword v175, v188, s[98:99] offset:512
	s_add_u32 s98, s38, 0x40000
	s_addc_u32 s99, s39, 0
	global_load_dword v176, v188, s[98:99]
	global_load_dword v177, v188, s[98:99] offset:512
	s_add_u32 s98, s38, 0x60000
	s_addc_u32 s99, s39, 0
	global_load_dword v178, v188, s[98:99]
	global_load_dword v179, v188, s[98:99] offset:512
	s_add_u32 s98, s38, 0x100000
	s_addc_u32 s99, s39, 0
	global_load_dword v180, v188, s[98:99]
	global_load_dword v181, v188, s[98:99] offset:512
	s_add_u32 s98, s38, 0x120000
	s_addc_u32 s99, s39, 0
	global_load_dword v182, v188, s[98:99]
	global_load_dword v183, v188, s[98:99] offset:512
	s_add_u32 s98, s38, 0x140000
	s_addc_u32 s99, s39, 0
	global_load_dword v184, v188, s[98:99]
	global_load_dword v185, v188, s[98:99] offset:512
	s_add_u32 s98, s38, 0x160000
	s_addc_u32 s99, s39, 0
	global_load_dword v186, v188, s[98:99]
	global_load_dword v187, v188, s[98:99] offset:512
	v_lshl_add_u64 v[128:129], v[154:155], 2, v[160:161]
	global_load_dwordx4 v[132:135], v[128:129], off offset:16
	s_nop 0
	global_load_dwordx4 v[128:131], v[128:129], off
	s_mov_b64 s[0:1], 0
	s_branch .LBB0_1944
